# ssm2 item->chunk mapping rotated by 16*(b>>1) so each workgroup half gets mixed carry-in (Horner) lengths instead of 4 items with the same chunk index
# speedup vs baseline: 1.0042x; 1.0042x over previous
; DI int tidx() { int t = threadIdx.x & 255; asm volatile("" : "+v"(t)); return t; }
; DI void ssm2_item(PREF p, int l, int item, unsigned char* ldsb) {
;   const int gq = item & 3, c = (item >> 2) & 63, b = item >> 8;
;   const int tid = tidx(), w = tid >> 6, lane = tid & 63;
;   const int g = gq * 4 + w;
;   float* uS = (float*)ldsb;
;   u16* Hs = (u16*)(ldsb + 16384) + w * (16 * 136);
;   __syncthreads();
;   ssm_stage_u(p, b, c, gq, uS);
;   __syncthreads();
;   const size_t pi = (size_t)(l * 16 + g) * 64 + lane;
;   float bre[16], bim[16];
; #pragma unroll
;   for (int j = 0; j < 16; ++j) { bre[j] = p.bbre[pi * 16 + j]; bim[j] = p.bbim[pi * 16 + j]; }
;   const float lr = p.lam[pi * 2], li = p.lam[pi * 2 + 1];
;   float pr = lr, pim = li;
; #pragma unroll
;   for (int q = 0; q < 6; ++q) { float a = pr * pr - pim * pim, bq = 2.f * pr * pim; pr = a; pim = bq; }
;   float hr = 0.f, hi = 0.f;
;   const float2* he = (const float2*)p.hend + ((size_t)(b * 16 + g) * 64) * 64 + lane;
;   {
;     for (int cc = 0; cc < c; cc += 16) {
.LBB0_268:
	s_lshr_b32 s0, s48, 9
	s_lshl_b32 s0, s0, 4
	s_lshr_b32 s63, s48, 2
	s_add_i32 s63, s63, s0
	s_and_b32 s63, s63, 63
	s_ashr_i32 s8, s48, 8
	v_mov_b32_e32 v79, v169
	v_mov_b32_e32 v0, v169
	s_lshl_b32 s0, s8, 12
	s_lshl_b32 s1, s63, 6
	s_barrier
	s_or_b32 s62, s1, s0
	s_load_dwordx2 s[0:1], s[10:11], 0x140
	v_ashrrev_i32_e32 v10, 2, v0
	v_lshlrev_b32_e32 v0, 4, v0
	s_and_b32 s9, s48, 3
	v_and_b32_e32 v11, 48, v0
	v_add_u32_e32 v0, s62, v10
	s_waitcnt lgkmcnt(0)
	v_mov_b64_e32 v[2:3], s[0:1]
	v_mad_i64_i32 v[2:3], s[0:1], v0, s60, v[2:3]
	s_lshl_b32 s52, s9, 7
	v_lshl_add_u64 v[2:3], v[2:3], 0, s[52:53]
	v_lshlrev_b32_e32 v0, 1, v11
	v_lshl_add_u64 v[6:7], v[2:3], 0, v[0:1]
	global_load_dwordx4 v[2:5], v[6:7], off offset:2880
	s_nop 0
	global_load_dwordx4 v[6:9], v[6:7], off offset:2896
	v_ashrrev_i32_e32 v80, 6, v79
	v_lshl_add_u32 v81, s9, 2, v80
	v_add_u32_e32 v22, s49, v81
	s_load_dwordx2 s[0:1], s[10:11], 0x118
	v_lshlrev_b32_e32 v0, 8, v10
	v_lshlrev_b32_e32 v10, 2, v11
	v_ashrrev_i32_e32 v23, 31, v22
	v_and_b32_e32 v78, 63, v79
	v_add3_u32 v0, s33, v0, v10
	v_lshlrev_b64 v[10:11], 6, v[22:23]
	v_or_b32_e32 v10, v10, v78
	v_lshlrev_b64 v[12:13], 6, v[10:11]
	v_lshl_add_u64 v[24:25], v[10:11], 3, s[40:41]
	v_lshl_add_u64 v[18:19], s[42:43], 0, v[12:13]
	s_waitcnt lgkmcnt(0)
	v_lshl_add_u64 v[20:21], s[0:1], 0, v[12:13]
	s_cmp_eq_u32 s63, 0
	s_waitcnt vmcnt(1)
	v_lshlrev_b32_e32 v10, 16, v2
	v_and_b32_e32 v11, 0xffff0000, v2
	v_lshlrev_b32_e32 v12, 16, v3
	v_and_b32_e32 v13, 0xffff0000, v3
	v_lshlrev_b32_e32 v2, 16, v4
	v_and_b32_e32 v3, 0xffff0000, v4
	v_lshlrev_b32_e32 v4, 16, v5
	v_and_b32_e32 v5, 0xffff0000, v5
	s_waitcnt vmcnt(0)
	v_lshlrev_b32_e32 v14, 16, v6
	v_and_b32_e32 v15, 0xffff0000, v6
	v_lshlrev_b32_e32 v16, 16, v7
	v_and_b32_e32 v17, 0xffff0000, v7
	v_lshlrev_b32_e32 v6, 16, v8
	v_and_b32_e32 v7, 0xffff0000, v8
	v_lshlrev_b32_e32 v8, 16, v9
	v_and_b32_e32 v9, 0xffff0000, v9
	ds_write_b128 v0, v[10:13]
	ds_write_b128 v0, v[2:5] offset:16
	ds_write_b128 v0, v[14:17] offset:32
	ds_write_b128 v0, v[6:9] offset:48
	s_waitcnt lgkmcnt(0)
	s_barrier
	global_load_dwordx4 v[42:45], v[18:19], off offset:48
	global_load_dwordx4 v[46:49], v[18:19], off offset:32
	global_load_dwordx4 v[2:5], v[18:19], off offset:16
	global_load_dwordx4 v[38:41], v[18:19], off
	global_load_dwordx4 v[6:9], v[20:21], off offset:48
	global_load_dwordx4 v[10:13], v[20:21], off offset:32
	global_load_dwordx4 v[14:17], v[20:21], off offset:16
	s_nop 0
	global_load_dwordx4 v[18:21], v[20:21], off
	s_nop 0
	global_load_dwordx2 v[50:51], v[24:25], off
	s_cbranch_scc1 .LBB0_302
	s_waitcnt vmcnt(0)
	v_pk_mul_f32 v[24:25], v[50:51], v[50:51]
	s_and_b32 s0, s57, 3
	v_sub_f32_e32 v0, v24, v25
	v_add_f32_e32 v24, v50, v50
	v_mul_f32_e32 v24, v51, v24
	v_mul_f32_e32 v25, v0, v0
	v_add_f32_e32 v0, v0, v0
	v_mul_f32_e32 v0, v24, v0
	v_fma_f32 v25, -v24, v24, v25
	v_mul_f32_e32 v24, v0, v0
	v_fma_f32 v24, v25, v25, -v24
	v_add_f32_e32 v25, v25, v25
	v_mul_f32_e32 v0, v0, v25
	v_mul_f32_e32 v25, v0, v0
	v_fma_f32 v25, v24, v24, -v25
	v_add_f32_e32 v24, v24, v24
	s_lshl_b32 s0, s0, 2
	v_mul_f32_e32 v0, v0, v24
	s_lshl_b32 s1, s8, 4
	v_mul_f32_e32 v24, v0, v0
	s_or_b32 s0, s0, s1
	v_fma_f32 v26, v25, v25, -v24
	v_add_f32_e32 v24, v25, v25
	v_add_u32_e32 v28, s0, v80
	v_mul_f32_e32 v0, v0, v24
	v_ashrrev_i32_e32 v29, 31, v28
	v_mul_f32_e32 v24, v0, v0
	v_add_f32_e32 v25, v26, v26
	v_lshlrev_b64 v[28:29], 15, v[28:29]
	v_fma_f32 v24, v26, v26, -v24
	v_mul_f32_e32 v26, v0, v25
	v_lshl_or_b32 v28, v78, 3, v28
	v_mov_b32_e32 v25, v24
	v_mov_b32_e32 v27, v26
	v_lshl_add_u64 v[28:29], s[68:69], 0, v[28:29]
	s_mov_b32 s52, 0
	v_mov_b32_e32 v52, 0
	v_mov_b32_e32 v53, 0
	s_branch .LBB0_271
